# speedup vs baseline: 1.0017x; 1.0017x over previous
; template <int NT, int BM, int BN, bool PLAIN, int NSTAGE, bool EPI_LDS>
; __device__ __forceinline__ void gemm_tile(const Params& p, const GemmDesc& g, bf16_t* lds, const int tid) {
;     ...
;   const int r0 = tid >> 3, c0 = tid & 7;
;   unsigned aoff[PLAIN ? 1 : NA];
;   const char* abase = (const char*)g.A;
;   if (PLAIN) {
;     abase = (const char*)(g.A + (long)m0 * g.lda_lo);
;     aoff[0] = (unsigned)((r0 * (int)g.lda_lo + c0 * 8) * 2);
;   } else {
; #pragma unroll
;     for (int i = 0; i < NA; ++i) {
;       int ra = m0 + r0 + RP * i;
;       int rlo = ra & g.rmask; rlo = rlo < g.rclamp ? rlo : g.rclamp;
;       aoff[i] = (unsigned)(((long)rlo * g.lda_lo + (long)(ra >> g.rshift) * g.lda_hi + c0 * 8) * 2);
;     }
;   }
;   const char* bbase = (const char*)(g.Bt + (long)n0 * g.ldb);
;   const unsigned boff = (unsigned)((r0 * (int)g.ldb + c0 * 8) * 2);
;   const long astepP = (long)RP * g.lda_lo * 2, bstepP = (long)RP * g.ldb * 2;
;   u32x4 ra4[NA], rb4[NB];
;   f32x4 acc[MI][NI];
; #pragma unroll
;   for (int i = 0; i < MI; ++i)
; #pragma unroll
;     for (int j = 0; j < NI; ++j) acc[i][j] = f32x4{0.f, 0.f, 0.f, 0.f};
;   const int nk = g.K >> 6;
;     ...
;   constexpr int STAGE_BYTES = (BM + BN) * 128;
;   char* const ldsb = (char*)lds;
;   const unsigned woff = (unsigned)(((r0 >> 4) * 2 + (c0 >> 2)) * 1024 + (((((r0 & 15) ^ (c0 >> 2)) * 64) + (c0 & 3) * 16) ^ (((r0 & 15) >> 3) << 5)));
;   const unsigned roff = (unsigned)(((fr * 64) + fq * 16) ^ ((fr >> 3) << 5));
;   const int roff1d = (int)((((fr ^ 1) * 64 + fq * 16) ^ ((fr >> 3) << 5))) - (int)roff;
;     ...
;     GLOAD(0)
;     __syncthreads();
;     LWRITE(0)
;     if (nk > 1) GLOAD(1)
;     __syncthreads();
.LBB0_896:
	v_lshrrev_b32_e32 v0, 6, v224
	v_and_b32_e32 v2, 63, v224
	v_readfirstlane_b32 s57, v0
	v_lshrrev_b32_e32 v3, 3, v2
	v_bfe_u32 v4, v2, 4, 2
	v_and_b32_e32 v5, 3, v2
	v_xor_b32_e32 v4, v4, v5
	v_lshlrev_b32_e32 v4, 4, v4
	v_bfe_u32 v5, v2, 2, 1
	v_lshl_or_b32 v4, v5, 6, v4
	v_xor_b32_e32 v5, 64, v4
	s_cmp_ge_u32 s57, 4
	s_cselect_b32 s58, s26, s52
	s_cselect_b32 s59, s41, s42
	s_cselect_b32 s60, s28, s30
	s_cselect_b32 s61, s29, s31
	s_cbranch_scc0 .Lmy_noprio
	s_setprio 1
.Lmy_noprio:
	s_and_b32 s62, s57, 3
	s_lshl_b32 s62, s62, 6
	s_add_i32 s59, s59, s62
	s_mul_i32 s59, s59, s58
	s_lshl_b32 s58, s58, 1
	s_lshl_b32 s59, s59, 1
	s_add_u32 s60, s60, s59
	s_addc_u32 s61, s61, 0
	v_mul_lo_u32 v3, v3, s58
	s_lshl_b32 s62, s58, 3
	v_add_u32_e32 v162, v3, v4
	v_add3_u32 v163, v3, v5, s62
	s_lshl_b32 s62, s58, 4
	v_add_u32_e32 v164, s62, v162
	v_add_u32_e32 v165, s62, v163
	v_add_u32_e32 v166, s62, v164
	v_add_u32_e32 v167, s62, v165
	v_add_u32_e32 v168, s62, v166
	v_add_u32_e32 v169, s62, v167
	s_lshl_b32 s57, s57, 13
	s_barrier
	s_mov_b32 m0, s57
	s_nop 0
	global_load_lds_dwordx4 v162, s[60:61]
	s_add_u32 m0, m0, 0x400
	s_nop 0
	global_load_lds_dwordx4 v163, s[60:61]
	s_add_u32 m0, m0, 0x400
	s_nop 0
	global_load_lds_dwordx4 v164, s[60:61]
	s_add_u32 m0, m0, 0x400
	s_nop 0
	global_load_lds_dwordx4 v165, s[60:61]
	s_add_u32 m0, m0, 0x400
	s_nop 0
	global_load_lds_dwordx4 v166, s[60:61]
	s_add_u32 m0, m0, 0x400
	s_nop 0
	global_load_lds_dwordx4 v167, s[60:61]
	s_add_u32 m0, m0, 0x400
	s_nop 0
	global_load_lds_dwordx4 v168, s[60:61]
	s_add_u32 m0, m0, 0x400
	s_nop 0
	global_load_lds_dwordx4 v169, s[60:61]
	s_add_u32 s60, s60, 0x80
	s_addc_u32 s61, s61, 0
	s_add_u32 m0, s57, 0x10000
	s_nop 0
	global_load_lds_dwordx4 v162, s[60:61]
	s_add_u32 m0, m0, 0x400
	s_nop 0
	global_load_lds_dwordx4 v163, s[60:61]
	s_add_u32 m0, m0, 0x400
	s_nop 0
	global_load_lds_dwordx4 v164, s[60:61]
	s_add_u32 m0, m0, 0x400
	s_nop 0
	global_load_lds_dwordx4 v165, s[60:61]
	v_mov_b32_e32 v110, 0
	v_mov_b32_e32 v111, v110
	v_mov_b32_e32 v112, v110
	v_mov_b32_e32 v113, v110
	v_mov_b32_e32 v90, v110
	v_mov_b32_e32 v91, v110
	v_mov_b32_e32 v92, v110
	v_mov_b32_e32 v93, v110
	v_mov_b32_e32 v40, v110
	v_mov_b32_e32 v41, v110
	v_mov_b32_e32 v42, v110
	v_mov_b32_e32 v43, v110
	v_mov_b32_e32 v44, v110
	v_mov_b32_e32 v45, v110
	v_mov_b32_e32 v46, v110
	v_mov_b32_e32 v47, v110
	v_mov_b32_e32 v48, v110
	v_mov_b32_e32 v49, v110
	v_mov_b32_e32 v50, v110
	v_mov_b32_e32 v51, v110
	v_mov_b32_e32 v52, v110
	v_mov_b32_e32 v53, v110
	v_mov_b32_e32 v54, v110
	v_mov_b32_e32 v55, v110
	v_mov_b32_e32 v56, v110
	v_mov_b32_e32 v57, v110
	v_mov_b32_e32 v58, v110
	v_mov_b32_e32 v59, v110
	v_mov_b32_e32 v60, v110
	v_mov_b32_e32 v61, v110
	v_mov_b32_e32 v62, v110
	v_mov_b32_e32 v63, v110
	v_mov_b32_e32 v64, v110
	v_mov_b32_e32 v65, v110
	v_mov_b32_e32 v66, v110
	v_mov_b32_e32 v67, v110
	v_mov_b32_e32 v68, v110
	v_mov_b32_e32 v69, v110
	v_mov_b32_e32 v70, v110
	v_mov_b32_e32 v71, v110
	v_mov_b32_e32 v72, v110
	v_mov_b32_e32 v73, v110
	v_mov_b32_e32 v74, v110
	v_mov_b32_e32 v75, v110
	v_mov_b32_e32 v76, v110
	v_mov_b32_e32 v34, v110
	v_mov_b32_e32 v35, v110
	v_mov_b32_e32 v36, v110
	v_mov_b32_e32 v37, v110
	v_mov_b32_e32 v38, v110
	v_mov_b32_e32 v39, v110
	v_mov_b32_e32 v77, v110
	v_mov_b32_e32 v78, v110
	v_mov_b32_e32 v79, v110
	v_mov_b32_e32 v80, v110
	v_mov_b32_e32 v81, v110
	v_mov_b32_e32 v82, v110
	v_mov_b32_e32 v83, v110
	v_mov_b32_e32 v84, v110
	v_mov_b32_e32 v85, v110
	v_mov_b32_e32 v86, v110
	v_mov_b32_e32 v87, v110
	v_mov_b32_e32 v88, v110
	v_mov_b32_e32 v89, v110
	v_mov_b32_e32 v94, v110
	v_mov_b32_e32 v95, v110
	v_mov_b32_e32 v96, v110
	v_mov_b32_e32 v97, v110
	v_mov_b32_e32 v98, v110
	v_mov_b32_e32 v99, v110
	v_mov_b32_e32 v100, v110
	v_mov_b32_e32 v101, v110
	v_mov_b32_e32 v102, v110
	v_mov_b32_e32 v103, v110
	v_mov_b32_e32 v104, v110
	v_mov_b32_e32 v105, v110
	v_mov_b32_e32 v106, v110
	v_mov_b32_e32 v107, v110
	v_mov_b32_e32 v108, v110
	v_mov_b32_e32 v109, v110
	v_mov_b32_e32 v114, v110
	v_mov_b32_e32 v115, v110
	v_mov_b32_e32 v116, v110
	v_mov_b32_e32 v117, v110
	v_mov_b32_e32 v118, v110
	v_mov_b32_e32 v119, v110
	v_mov_b32_e32 v120, v110
	v_mov_b32_e32 v121, v110
	v_mov_b32_e32 v122, v110
	v_mov_b32_e32 v123, v110
	v_mov_b32_e32 v124, v110
	v_mov_b32_e32 v125, v110
	v_mov_b32_e32 v126, v110
	v_mov_b32_e32 v127, v110
	v_mov_b32_e32 v128, v110
	v_mov_b32_e32 v129, v110
	v_mov_b32_e32 v130, v110
	v_mov_b32_e32 v131, v110
	v_mov_b32_e32 v132, v110
	v_mov_b32_e32 v133, v110
	v_mov_b32_e32 v134, v110
	v_mov_b32_e32 v135, v110
	v_mov_b32_e32 v136, v110
	v_mov_b32_e32 v137, v110
	v_mov_b32_e32 v138, v110
	v_mov_b32_e32 v139, v110
	v_mov_b32_e32 v140, v110
	v_mov_b32_e32 v141, v110
	v_mov_b32_e32 v142, v110
	v_mov_b32_e32 v143, v110
	v_mov_b32_e32 v144, v110
	v_mov_b32_e32 v145, v110
	v_mov_b32_e32 v146, v110
	v_mov_b32_e32 v147, v110
	v_mov_b32_e32 v148, v110
	v_mov_b32_e32 v149, v110
	v_mov_b32_e32 v150, v110
	v_mov_b32_e32 v151, v110
	v_mov_b32_e32 v152, v110
	v_mov_b32_e32 v153, v110
	v_mov_b32_e32 v154, v110
	v_mov_b32_e32 v155, v110
	v_mov_b32_e32 v156, v110
	v_mov_b32_e32 v157, v110
	v_mov_b32_e32 v158, v110
	v_mov_b32_e32 v159, v110
	v_mov_b32_e32 v160, v110
	v_mov_b32_e32 v161, v110
	s_add_i32 s3, s23, -2
	s_mov_b32 s26, 0
	s_mov_b32 s27, s3
	s_waitcnt vmcnt(4)
	s_barrier
	v_add_u32_e32 v19, v180, v184
	v_add_u32_e32 v18, v180, v183
	ds_read_b128 v[2:5], v19 offset:32768
	ds_read_b128 v[6:9], v19 offset:34816
	ds_read_b128 v[10:13], v19 offset:36864
	ds_read_b128 v[14:17], v19 offset:38912
	ds_read_b128 v[202:205], v18
	ds_read_b128 v[206:209], v18 offset:2048
	ds_read_b128 v[226:229], v18 offset:4096
	.p2align 6
.LBB0_897:
	s_and_b32 s28, s26, 0x10000
	s_xor_b32 s29, s28, 0x10000
	s_add_u32 m0, s29, s57
	s_add_u32 m0, m0, 0x1000
	v_or_b32_e32 v0, s28, v180
	v_add_u32_e32 v218, v0, v184
	v_add_u32_e32 v0, v0, v183
	s_waitcnt lgkmcnt(2)
	v_mfma_f32_16x16x32_bf16 v[158:161], v[2:5], v[202:205], v[158:161]
	global_load_lds_dwordx4 v166, s[60:61]
	s_add_u32 m0, m0, 0x400
	v_add_u32_e32 v218, v218, v181
	s_add_i32 s27, s27, -1
	v_mfma_f32_16x16x32_bf16 v[154:157], v[6:9], v[202:205], v[154:157]
	s_add_i32 s26, s26, 0x10000
	v_mfma_f32_16x16x32_bf16 v[150:153], v[10:13], v[202:205], v[150:153]
	global_load_lds_dwordx4 v167, s[60:61]
	s_add_u32 m0, m0, 0x400
	v_mfma_f32_16x16x32_bf16 v[146:149], v[14:17], v[202:205], v[146:149]
	ds_read_b128 v[202:205], v0 offset:6144
	s_waitcnt lgkmcnt(2)
	v_mfma_f32_16x16x32_bf16 v[142:145], v[2:5], v[206:209], v[142:145]
	global_load_lds_dwordx4 v168, s[60:61]
	s_add_u32 m0, m0, 0x400
	v_mfma_f32_16x16x32_bf16 v[138:141], v[6:9], v[206:209], v[138:141]
	v_mfma_f32_16x16x32_bf16 v[134:137], v[10:13], v[206:209], v[134:137]
	global_load_lds_dwordx4 v169, s[60:61]
	s_add_u32 s60, s60, 0x80
	s_addc_u32 s61, s61, 0
	v_mfma_f32_16x16x32_bf16 v[130:133], v[14:17], v[206:209], v[130:133]
	ds_read_b128 v[206:209], v0 offset:8192
	s_waitcnt lgkmcnt(2)
	v_mfma_f32_16x16x32_bf16 v[126:129], v[2:5], v[226:229], v[126:129]
	v_mfma_f32_16x16x32_bf16 v[122:125], v[6:9], v[226:229], v[122:125]
	v_mfma_f32_16x16x32_bf16 v[118:121], v[10:13], v[226:229], v[118:121]
	v_mfma_f32_16x16x32_bf16 v[114:117], v[14:17], v[226:229], v[114:117]
	ds_read_b128 v[226:229], v0 offset:10240
	s_waitcnt lgkmcnt(2)
	v_mfma_f32_16x16x32_bf16 v[106:109], v[2:5], v[202:205], v[106:109]
	v_mfma_f32_16x16x32_bf16 v[102:105], v[6:9], v[202:205], v[102:105]
	v_mfma_f32_16x16x32_bf16 v[98:101], v[10:13], v[202:205], v[98:101]
	v_mfma_f32_16x16x32_bf16 v[94:97], v[14:17], v[202:205], v[94:97]
	ds_read_b128 v[202:205], v0 offset:12288
	ds_read_b128 v[230:233], v218 offset:32768
	s_waitcnt lgkmcnt(3)
	v_mfma_f32_16x16x32_bf16 v[86:89], v[2:5], v[206:209], v[86:89]
	v_mfma_f32_16x16x32_bf16 v[82:85], v[6:9], v[206:209], v[82:85]
	v_mfma_f32_16x16x32_bf16 v[78:81], v[10:13], v[206:209], v[78:81]
	v_mfma_f32_16x16x32_bf16 v[74:77], v[14:17], v[206:209], v[74:77]
	ds_read_b128 v[206:209], v0 offset:14336
	ds_read_b128 v[234:237], v218 offset:34816
	v_add_u32_e32 v0, v0, v181
	s_waitcnt lgkmcnt(4)
	v_mfma_f32_16x16x32_bf16 v[70:73], v[2:5], v[226:229], v[70:73]
	v_mfma_f32_16x16x32_bf16 v[66:69], v[6:9], v[226:229], v[66:69]
	v_mfma_f32_16x16x32_bf16 v[62:65], v[10:13], v[226:229], v[62:65]
	v_mfma_f32_16x16x32_bf16 v[58:61], v[14:17], v[226:229], v[58:61]
	ds_read_b128 v[226:229], v0 offset:0
	ds_read_b128 v[238:241], v218 offset:36864
	s_waitcnt lgkmcnt(5)
	v_mfma_f32_16x16x32_bf16 v[54:57], v[2:5], v[202:205], v[54:57]
	v_mfma_f32_16x16x32_bf16 v[50:53], v[6:9], v[202:205], v[50:53]
	v_mfma_f32_16x16x32_bf16 v[46:49], v[10:13], v[202:205], v[46:49]
	v_mfma_f32_16x16x32_bf16 v[42:45], v[14:17], v[202:205], v[42:45]
	ds_read_b128 v[202:205], v0 offset:2048
	ds_read_b128 v[242:245], v218 offset:38912
	s_waitcnt lgkmcnt(5)
	v_mfma_f32_16x16x32_bf16 v[38:41], v[2:5], v[206:209], v[38:41]
	v_mfma_f32_16x16x32_bf16 v[34:37], v[6:9], v[206:209], v[34:37]
	v_mfma_f32_16x16x32_bf16 v[90:93], v[10:13], v[206:209], v[90:93]
	v_mfma_f32_16x16x32_bf16 v[110:113], v[14:17], v[206:209], v[110:113]
	ds_read_b128 v[186:189], v0 offset:4096
	s_waitcnt lgkmcnt(4)
	v_mfma_f32_16x16x32_bf16 v[158:161], v[230:233], v[226:229], v[158:161]
	v_mfma_f32_16x16x32_bf16 v[154:157], v[234:237], v[226:229], v[154:157]
	s_waitcnt lgkmcnt(3)
	v_mfma_f32_16x16x32_bf16 v[150:153], v[238:241], v[226:229], v[150:153]
	s_waitcnt lgkmcnt(1)
	v_mfma_f32_16x16x32_bf16 v[146:149], v[242:245], v[226:229], v[146:149]
	ds_read_b128 v[190:193], v0 offset:6144
	v_mfma_f32_16x16x32_bf16 v[142:145], v[230:233], v[202:205], v[142:145]
	v_mfma_f32_16x16x32_bf16 v[138:141], v[234:237], v[202:205], v[138:141]
	v_mfma_f32_16x16x32_bf16 v[134:137], v[238:241], v[202:205], v[134:137]
	v_mfma_f32_16x16x32_bf16 v[130:133], v[242:245], v[202:205], v[130:133]
	ds_read_b128 v[194:197], v0 offset:8192
	s_waitcnt lgkmcnt(2)
	v_mfma_f32_16x16x32_bf16 v[126:129], v[230:233], v[186:189], v[126:129]
	v_mfma_f32_16x16x32_bf16 v[122:125], v[234:237], v[186:189], v[122:125]
	v_mfma_f32_16x16x32_bf16 v[118:121], v[238:241], v[186:189], v[118:121]
	v_mfma_f32_16x16x32_bf16 v[114:117], v[242:245], v[186:189], v[114:117]
	ds_read_b128 v[186:189], v0 offset:10240
	s_waitcnt lgkmcnt(2)
	v_mfma_f32_16x16x32_bf16 v[106:109], v[230:233], v[190:193], v[106:109]
	v_mfma_f32_16x16x32_bf16 v[102:105], v[234:237], v[190:193], v[102:105]
	v_mfma_f32_16x16x32_bf16 v[98:101], v[238:241], v[190:193], v[98:101]
	v_mfma_f32_16x16x32_bf16 v[94:97], v[242:245], v[190:193], v[94:97]
	ds_read_b128 v[190:193], v0 offset:12288
	s_waitcnt lgkmcnt(2)
	v_mfma_f32_16x16x32_bf16 v[86:89], v[230:233], v[194:197], v[86:89]
	v_mfma_f32_16x16x32_bf16 v[82:85], v[234:237], v[194:197], v[82:85]
	v_mfma_f32_16x16x32_bf16 v[78:81], v[238:241], v[194:197], v[78:81]
	v_mfma_f32_16x16x32_bf16 v[74:77], v[242:245], v[194:197], v[74:77]
	ds_read_b128 v[194:197], v0 offset:14336
	s_waitcnt lgkmcnt(2)
	v_mfma_f32_16x16x32_bf16 v[70:73], v[230:233], v[186:189], v[70:73]
	v_mfma_f32_16x16x32_bf16 v[66:69], v[234:237], v[186:189], v[66:69]
	v_mfma_f32_16x16x32_bf16 v[62:65], v[238:241], v[186:189], v[62:65]
	v_mfma_f32_16x16x32_bf16 v[58:61], v[242:245], v[186:189], v[58:61]
	s_waitcnt vmcnt(0) lgkmcnt(0)
	s_barrier
; template <int NT, int BM, int BN, bool PLAIN, int NSTAGE, bool EPI_LDS>
; __device__ __forceinline__ void gemm_tile(const Params& p, const GemmDesc& g, bf16_t* lds, const int tid) {
;     ...
;     if (PLAIN) {
;       int kt = 0;
;       for (; kt + 2 < nk; ++kt) {
;         const int cur = kt & 1;
;         COMPUTE_X(cur, 1, 1, kt + 2)
;         __syncthreads();
;       }
;       if (kt + 1 < nk) {
;         const int cur = kt & 1;
;         COMPUTE_X(cur, 1, 0, 0)
;         __syncthreads();
;         ++kt;
;       }
;       {
;         const int cur = kt & 1;
;         COMPUTE_X(cur, 0, 0, 0)
;         __syncthreads();
	s_xor_b32 s29, s28, 0x10000
	v_or_b32_e32 v18, s29, v180
	v_add_u32_e32 v19, v18, v184
	v_add_u32_e32 v18, v18, v183
	ds_read_b128 v[2:5], v19 offset:32768
	ds_read_b128 v[6:9], v19 offset:34816
	ds_read_b128 v[10:13], v19 offset:36864
	ds_read_b128 v[14:17], v19 offset:38912
	ds_read_b128 v[202:205], v18
	ds_read_b128 v[206:209], v18 offset:2048
	ds_read_b128 v[226:229], v18 offset:4096
	s_add_u32 m0, s28, s57
	v_mfma_f32_16x16x32_bf16 v[54:57], v[230:233], v[190:193], v[54:57]
	global_load_lds_dwordx4 v162, s[60:61]
	s_add_u32 m0, m0, 0x400
	v_mfma_f32_16x16x32_bf16 v[50:53], v[234:237], v[190:193], v[50:53]
	v_mfma_f32_16x16x32_bf16 v[46:49], v[238:241], v[190:193], v[46:49]
	global_load_lds_dwordx4 v163, s[60:61]
	s_add_u32 m0, m0, 0x400
	v_mfma_f32_16x16x32_bf16 v[42:45], v[242:245], v[190:193], v[42:45]
	v_mfma_f32_16x16x32_bf16 v[38:41], v[230:233], v[194:197], v[38:41]
	global_load_lds_dwordx4 v164, s[60:61]
	s_add_u32 m0, m0, 0x400
	v_mfma_f32_16x16x32_bf16 v[34:37], v[234:237], v[194:197], v[34:37]
	v_mfma_f32_16x16x32_bf16 v[90:93], v[238:241], v[194:197], v[90:93]
	global_load_lds_dwordx4 v165, s[60:61]
	v_mfma_f32_16x16x32_bf16 v[110:113], v[242:245], v[194:197], v[110:113]
	s_cmp_lg_u32 s27, 0
	s_cbranch_scc1 .LBB0_897
	s_setprio 0
	s_lshl_b32 s3, s3, 16
	s_and_b32 s3, s3, 0x10000
	s_xor_b32 s29, s3, 0x10000
	s_add_u32 m0, s29, s57
	s_add_u32 m0, m0, 0x1000
	s_nop 0
	global_load_lds_dwordx4 v166, s[60:61]
	s_add_u32 m0, m0, 0x400
	s_nop 0
	global_load_lds_dwordx4 v167, s[60:61]
	s_add_u32 m0, m0, 0x400
	s_nop 0
	global_load_lds_dwordx4 v168, s[60:61]
	s_add_u32 m0, m0, 0x400
	s_nop 0
	global_load_lds_dwordx4 v169, s[60:61]
	v_or_b32_e32 v0, s3, v180
	v_add_u32_e32 v198, v0, v184
	ds_read_b128 v[162:165], v198 offset:32768
	ds_read_b128 v[166:169], v198 offset:34816
	ds_read_b128 v[170:173], v198 offset:36864
	ds_read_b128 v[186:189], v198 offset:38912
	v_add_u32_e32 v0, v0, v183
	ds_read_b128 v[174:177], v0
	ds_read_b128 v[190:193], v0 offset:2048
	ds_read_b128 v[194:197], v0 offset:4096
	s_waitcnt lgkmcnt(2)
	v_mfma_f32_16x16x32_bf16 v[30:33], v[162:165], v[174:177], v[158:161]
	s_not_b32 s3, s23
	s_lshl_b32 s3, s3, 16
	s_and_b32 s3, s3, 0x10000
	v_mfma_f32_16x16x32_bf16 v[154:157], v[166:169], v[174:177], v[154:157]
	s_cmp_lg_u32 s56, 9
	s_cselect_b64 s[26:27], -1, 0
	s_mov_b32 s24, s41
	v_mfma_f32_16x16x32_bf16 v[150:153], v[170:173], v[174:177], v[150:153]
	s_mov_b32 s23, s42
	s_mov_b64 s[28:29], -1
	s_and_b64 vcc, exec, s[26:27]
	v_mfma_f32_16x16x32_bf16 v[146:149], v[186:189], v[174:177], v[146:149]
	ds_read_b128 v[158:161], v0 offset:6144
	v_add_u32_e32 v174, v198, v181
	s_waitcnt lgkmcnt(2)
	v_mfma_f32_16x16x32_bf16 v[26:29], v[162:165], v[190:193], v[142:145]
	v_mfma_f32_16x16x32_bf16 v[138:141], v[166:169], v[190:193], v[138:141]
	v_mfma_f32_16x16x32_bf16 v[134:137], v[170:173], v[190:193], v[134:137]
	v_mfma_f32_16x16x32_bf16 v[130:133], v[186:189], v[190:193], v[130:133]
	ds_read_b128 v[142:145], v0 offset:8192
	s_waitcnt lgkmcnt(2)
	v_mfma_f32_16x16x32_bf16 v[22:25], v[162:165], v[194:197], v[126:129]
	v_mfma_f32_16x16x32_bf16 v[122:125], v[166:169], v[194:197], v[122:125]
	v_mfma_f32_16x16x32_bf16 v[118:121], v[170:173], v[194:197], v[118:121]
	v_mfma_f32_16x16x32_bf16 v[114:117], v[186:189], v[194:197], v[114:117]
	ds_read_b128 v[126:129], v0 offset:10240
	s_waitcnt lgkmcnt(2)
	v_mfma_f32_16x16x32_bf16 v[18:21], v[162:165], v[158:161], v[106:109]
	v_mfma_f32_16x16x32_bf16 v[102:105], v[166:169], v[158:161], v[102:105]
	v_mfma_f32_16x16x32_bf16 v[98:101], v[170:173], v[158:161], v[98:101]
	v_mfma_f32_16x16x32_bf16 v[94:97], v[186:189], v[158:161], v[94:97]
	ds_read_b128 v[106:109], v0 offset:12288
	ds_read_b128 v[158:161], v174 offset:32768
	s_waitcnt lgkmcnt(3)
	v_mfma_f32_16x16x32_bf16 v[14:17], v[162:165], v[142:145], v[86:89]
	v_mfma_f32_16x16x32_bf16 v[82:85], v[166:169], v[142:145], v[82:85]
	v_mfma_f32_16x16x32_bf16 v[78:81], v[170:173], v[142:145], v[78:81]
	v_mfma_f32_16x16x32_bf16 v[74:77], v[186:189], v[142:145], v[74:77]
	ds_read_b128 v[86:89], v0 offset:14336
	ds_read_b128 v[142:145], v174 offset:34816
	v_add_u32_e32 v0, v0, v181
	s_waitcnt lgkmcnt(4)
	v_mfma_f32_16x16x32_bf16 v[10:13], v[162:165], v[126:129], v[70:73]
	v_mfma_f32_16x16x32_bf16 v[66:69], v[166:169], v[126:129], v[66:69]
	v_mfma_f32_16x16x32_bf16 v[62:65], v[170:173], v[126:129], v[62:65]
	v_mfma_f32_16x16x32_bf16 v[58:61], v[186:189], v[126:129], v[58:61]
	ds_read_b128 v[70:73], v0 offset:0
	ds_read_b128 v[126:129], v174 offset:36864
	s_waitcnt lgkmcnt(5)
	v_mfma_f32_16x16x32_bf16 v[6:9], v[162:165], v[106:109], v[54:57]
	v_mfma_f32_16x16x32_bf16 v[50:53], v[166:169], v[106:109], v[50:53]
	v_mfma_f32_16x16x32_bf16 v[46:49], v[170:173], v[106:109], v[46:49]
	v_mfma_f32_16x16x32_bf16 v[42:45], v[186:189], v[106:109], v[42:45]
	ds_read_b128 v[106:109], v174 offset:38912
	ds_read_b128 v[54:57], v0 offset:2048
	s_waitcnt lgkmcnt(5)
	v_mfma_f32_16x16x32_bf16 v[2:5], v[162:165], v[86:89], v[38:41]
	v_mfma_f32_16x16x32_bf16 v[34:37], v[166:169], v[86:89], v[34:37]
	v_mfma_f32_16x16x32_bf16 v[38:41], v[170:173], v[86:89], v[90:93]
	v_mfma_f32_16x16x32_bf16 v[86:89], v[186:189], v[86:89], v[110:113]
	s_nop 1
	ds_read_b128 v[90:93], v0 offset:4096
	s_waitcnt lgkmcnt(4)
	v_mfma_f32_16x16x32_bf16 v[30:33], v[158:161], v[70:73], v[30:33]
	v_mfma_f32_16x16x32_bf16 v[110:113], v[142:145], v[70:73], v[154:157]
	s_waitcnt lgkmcnt(3)
	v_mfma_f32_16x16x32_bf16 v[150:153], v[126:129], v[70:73], v[150:153]
	s_waitcnt lgkmcnt(2)
	v_mfma_f32_16x16x32_bf16 v[70:73], v[106:109], v[70:73], v[146:149]
	s_nop 2
	ds_read_b128 v[146:149], v0 offset:6144
	s_waitcnt lgkmcnt(2)
	v_mfma_f32_16x16x32_bf16 v[26:29], v[158:161], v[54:57], v[26:29]
	v_mfma_f32_16x16x32_bf16 v[138:141], v[142:145], v[54:57], v[138:141]
	v_mfma_f32_16x16x32_bf16 v[134:137], v[126:129], v[54:57], v[134:137]
	v_mfma_f32_16x16x32_bf16 v[54:57], v[106:109], v[54:57], v[130:133]
	s_nop 2
	ds_read_b128 v[130:133], v0 offset:8192
	s_waitcnt lgkmcnt(2)
	v_mfma_f32_16x16x32_bf16 v[22:25], v[158:161], v[90:93], v[22:25]
	v_mfma_f32_16x16x32_bf16 v[122:125], v[142:145], v[90:93], v[122:125]
	v_mfma_f32_16x16x32_bf16 v[118:121], v[126:129], v[90:93], v[118:121]
	v_mfma_f32_16x16x32_bf16 v[90:93], v[106:109], v[90:93], v[114:117]
	s_nop 2
	ds_read_b128 v[114:117], v0 offset:10240
	s_waitcnt lgkmcnt(2)
	v_mfma_f32_16x16x32_bf16 v[18:21], v[158:161], v[146:149], v[18:21]
	v_mfma_f32_16x16x32_bf16 v[102:105], v[142:145], v[146:149], v[102:105]
	v_mfma_f32_16x16x32_bf16 v[98:101], v[126:129], v[146:149], v[98:101]
	v_mfma_f32_16x16x32_bf16 v[94:97], v[106:109], v[146:149], v[94:97]
	ds_read_b128 v[146:149], v0 offset:12288
	s_waitcnt lgkmcnt(2)
	v_mfma_f32_16x16x32_bf16 v[14:17], v[158:161], v[130:133], v[14:17]
	v_mfma_f32_16x16x32_bf16 v[82:85], v[142:145], v[130:133], v[82:85]
	v_mfma_f32_16x16x32_bf16 v[78:81], v[126:129], v[130:133], v[78:81]
	v_mfma_f32_16x16x32_bf16 v[74:77], v[106:109], v[130:133], v[74:77]
	ds_read_b128 v[130:133], v0 offset:14336
	v_or_b32_e32 v0, s3, v180
	v_add_u32_e32 v186, v0, v184
	s_waitcnt lgkmcnt(2)
	v_mfma_f32_16x16x32_bf16 v[10:13], v[158:161], v[114:117], v[10:13]
	s_waitcnt vmcnt(0) lgkmcnt(0)
	s_barrier
; template <int NT, int BM, int BN, bool PLAIN, int NSTAGE, bool EPI_LDS>
; __device__ __forceinline__ void gemm_tile(const Params& p, const GemmDesc& g, bf16_t* lds, const int tid) {
;     ...
;   if (EPI_LDS) {
;     constexpr int CST = BN + 16;
;     bf16_t* ct = lds;
;     const bool relu2 = (g.epi == E_RELU2);
; #pragma unroll
;     for (int mi = 0; mi < MI; ++mi)
; #pragma unroll
;       for (int ni = 0; ni < NI; ++ni) {
;         f32x4 v = acc[mi][ni];
;         if (relu2) {
; #pragma unroll
;           for (int j = 0; j < 4; ++j) { const float r = fmaxf(v[j], 0.f); v[j] = r * r; }
;         }
;         u32x2 w;
;         w[0] = pack2(v[0], v[1]);
;         w[1] = pack2(v[2], v[3]);
;         *(u32x2*)(ct + (wm * WTM + mi * 16 + fr) * CST + wn * WTN + ni * 16 + fq * 4) = w;
	v_mfma_f32_16x16x32_bf16 v[66:69], v[142:145], v[114:117], v[66:69]
	v_add_u32_e32 v0, v0, v183
	v_mfma_f32_16x16x32_bf16 v[62:65], v[126:129], v[114:117], v[62:65]
	v_mfma_f32_16x16x32_bf16 v[58:61], v[106:109], v[114:117], v[58:61]
	v_mfma_f32_16x16x32_bf16 v[6:9], v[158:161], v[146:149], v[6:9]
	v_mfma_f32_16x16x32_bf16 v[50:53], v[142:145], v[146:149], v[50:53]
	v_mfma_f32_16x16x32_bf16 v[46:49], v[126:129], v[146:149], v[46:49]
	v_mfma_f32_16x16x32_bf16 v[42:45], v[106:109], v[146:149], v[42:45]
	v_mfma_f32_16x16x32_bf16 v[2:5], v[158:161], v[130:133], v[2:5]
	v_mfma_f32_16x16x32_bf16 v[34:37], v[142:145], v[130:133], v[34:37]
	v_mfma_f32_16x16x32_bf16 v[38:41], v[126:129], v[130:133], v[38:41]
	v_mfma_f32_16x16x32_bf16 v[86:89], v[106:109], v[130:133], v[86:89]
	ds_read_b128 v[106:109], v186 offset:32768
	ds_read_b128 v[114:117], v186 offset:34816
	ds_read_b128 v[130:133], v186 offset:36864
	ds_read_b128 v[142:145], v186 offset:38912
	ds_read_b128 v[126:129], v0
	ds_read_b128 v[146:149], v0 offset:2048
	ds_read_b128 v[154:157], v0 offset:4096
	s_waitcnt lgkmcnt(2)
	v_mfma_f32_16x16x32_bf16 v[30:33], v[106:109], v[126:129], v[30:33]
	v_mfma_f32_16x16x32_bf16 v[110:113], v[114:117], v[126:129], v[110:113]
	v_mfma_f32_16x16x32_bf16 v[150:153], v[130:133], v[126:129], v[150:153]
	v_mfma_f32_16x16x32_bf16 v[70:73], v[142:145], v[126:129], v[70:73]
	ds_read_b128 v[126:129], v0 offset:6144
	s_waitcnt lgkmcnt(2)
	v_mfma_f32_16x16x32_bf16 v[26:29], v[106:109], v[146:149], v[26:29]
	v_mfma_f32_16x16x32_bf16 v[138:141], v[114:117], v[146:149], v[138:141]
	v_mfma_f32_16x16x32_bf16 v[134:137], v[130:133], v[146:149], v[134:137]
	v_mfma_f32_16x16x32_bf16 v[54:57], v[142:145], v[146:149], v[54:57]
	ds_read_b128 v[146:149], v0 offset:8192
	s_waitcnt lgkmcnt(2)
	v_mfma_f32_16x16x32_bf16 v[22:25], v[106:109], v[154:157], v[22:25]
	v_mfma_f32_16x16x32_bf16 v[158:161], v[114:117], v[154:157], v[122:125]
	v_mfma_f32_16x16x32_bf16 v[162:165], v[130:133], v[154:157], v[118:121]
	v_mfma_f32_16x16x32_bf16 v[154:157], v[142:145], v[154:157], v[90:93]
	s_nop 2
	ds_read_b128 v[90:93], v0 offset:10240
	s_waitcnt lgkmcnt(2)
	v_mfma_f32_16x16x32_bf16 v[18:21], v[106:109], v[126:129], v[18:21]
	v_mfma_f32_16x16x32_bf16 v[166:169], v[114:117], v[126:129], v[102:105]
	v_mfma_f32_16x16x32_bf16 v[170:173], v[130:133], v[126:129], v[98:101]
	v_mfma_f32_16x16x32_bf16 v[174:177], v[142:145], v[126:129], v[94:97]
	s_nop 1
	v_add_u32_e32 v98, v186, v181
	ds_read_b128 v[186:189], v98 offset:32768
	ds_read_b128 v[94:97], v0 offset:12288
	s_waitcnt lgkmcnt(3)
	v_mfma_f32_16x16x32_bf16 v[14:17], v[106:109], v[146:149], v[14:17]
	v_mfma_f32_16x16x32_bf16 v[190:193], v[114:117], v[146:149], v[82:85]
	v_mfma_f32_16x16x32_bf16 v[194:197], v[130:133], v[146:149], v[78:81]
	v_mfma_f32_16x16x32_bf16 v[146:149], v[142:145], v[146:149], v[74:77]
	ds_read_b128 v[198:201], v98 offset:34816
	s_nop 1
	ds_read_b128 v[74:77], v0 offset:14336
	v_add_u32_e32 v0, v0, v181
	s_waitcnt lgkmcnt(4)
	v_mfma_f32_16x16x32_bf16 v[10:13], v[106:109], v[90:93], v[10:13]
	v_mfma_f32_16x16x32_bf16 v[202:205], v[114:117], v[90:93], v[66:69]
	v_mfma_f32_16x16x32_bf16 v[206:209], v[130:133], v[90:93], v[62:65]
	v_mfma_f32_16x16x32_bf16 v[226:229], v[142:145], v[90:93], v[58:61]
	ds_read_b128 v[230:233], v98 offset:36864
	s_nop 1
	ds_read_b128 v[58:61], v0 offset:0
	s_waitcnt lgkmcnt(4)
	v_mfma_f32_16x16x32_bf16 v[6:9], v[106:109], v[94:97], v[6:9]
	v_mfma_f32_16x16x32_bf16 v[234:237], v[114:117], v[94:97], v[50:53]
	v_mfma_f32_16x16x32_bf16 v[238:241], v[130:133], v[94:97], v[46:49]
	v_mfma_f32_16x16x32_bf16 v[242:245], v[142:145], v[94:97], v[42:45]
	ds_read_b128 v[246:249], v98 offset:38912
	s_nop 1
	ds_read_b128 v[42:45], v0 offset:2048
	s_waitcnt lgkmcnt(4)
	v_mfma_f32_16x16x32_bf16 v[2:5], v[106:109], v[74:77], v[2:5]
	v_mfma_f32_16x16x32_bf16 v[218:221], v[114:117], v[74:77], v[34:37]
	v_mfma_f32_16x16x32_bf16 v[130:133], v[130:133], v[74:77], v[38:41]
	v_mfma_f32_16x16x32_bf16 v[142:145], v[142:145], v[74:77], v[86:89]
	s_nop 0
	ds_read_b128 v[34:37], v0 offset:4096
	s_waitcnt lgkmcnt(3)
	v_mfma_f32_16x16x32_bf16 v[126:129], v[186:189], v[58:61], v[30:33]
	v_mfma_f32_16x16x32_bf16 v[122:125], v[198:201], v[58:61], v[110:113]
	v_mfma_f32_16x16x32_bf16 v[118:121], v[230:233], v[58:61], v[150:153]
	s_waitcnt lgkmcnt(2)
	v_mfma_f32_16x16x32_bf16 v[114:117], v[246:249], v[58:61], v[70:73]
	ds_read_b128 v[30:33], v0 offset:6144
	s_waitcnt lgkmcnt(2)
	v_mfma_f32_16x16x32_bf16 v[110:113], v[186:189], v[42:45], v[26:29]
	v_mfma_f32_16x16x32_bf16 v[106:109], v[198:201], v[42:45], v[138:141]
	v_mfma_f32_16x16x32_bf16 v[102:105], v[230:233], v[42:45], v[134:137]
	v_mfma_f32_16x16x32_bf16 v[98:101], v[246:249], v[42:45], v[54:57]
	ds_read_b128 v[26:29], v0 offset:8192
	s_waitcnt lgkmcnt(2)
	v_mfma_f32_16x16x32_bf16 v[94:97], v[186:189], v[34:37], v[22:25]
	v_mfma_f32_16x16x32_bf16 v[90:93], v[198:201], v[34:37], v[158:161]
	v_mfma_f32_16x16x32_bf16 v[86:89], v[230:233], v[34:37], v[162:165]
	v_mfma_f32_16x16x32_bf16 v[82:85], v[246:249], v[34:37], v[154:157]
	ds_read_b128 v[22:25], v0 offset:10240
	s_waitcnt lgkmcnt(2)
	v_mfma_f32_16x16x32_bf16 v[78:81], v[186:189], v[30:33], v[18:21]
	v_mfma_f32_16x16x32_bf16 v[74:77], v[198:201], v[30:33], v[166:169]
	v_mfma_f32_16x16x32_bf16 v[70:73], v[230:233], v[30:33], v[170:173]
	v_mfma_f32_16x16x32_bf16 v[66:69], v[246:249], v[30:33], v[174:177]
	ds_read_b128 v[18:21], v0 offset:12288
	s_waitcnt lgkmcnt(2)
	v_mfma_f32_16x16x32_bf16 v[62:65], v[186:189], v[26:29], v[14:17]
	v_mfma_f32_16x16x32_bf16 v[58:61], v[198:201], v[26:29], v[190:193]
	v_mfma_f32_16x16x32_bf16 v[54:57], v[230:233], v[26:29], v[194:197]
	v_mfma_f32_16x16x32_bf16 v[50:53], v[246:249], v[26:29], v[146:149]
	ds_read_b128 v[134:137], v0 offset:14336
	s_waitcnt lgkmcnt(0)
	s_barrier
	v_mfma_f32_16x16x32_bf16 v[46:49], v[186:189], v[22:25], v[10:13]
	v_mfma_f32_16x16x32_bf16 v[42:45], v[198:201], v[22:25], v[202:205]
	v_mfma_f32_16x16x32_bf16 v[38:41], v[230:233], v[22:25], v[206:209]
	v_mfma_f32_16x16x32_bf16 v[34:37], v[246:249], v[22:25], v[226:229]
	v_mfma_f32_16x16x32_bf16 v[30:33], v[186:189], v[18:21], v[6:9]
	v_mfma_f32_16x16x32_bf16 v[26:29], v[198:201], v[18:21], v[234:237]
	v_mfma_f32_16x16x32_bf16 v[22:25], v[230:233], v[18:21], v[238:241]
	v_mfma_f32_16x16x32_bf16 v[18:21], v[246:249], v[18:21], v[242:245]
	v_mfma_f32_16x16x32_bf16 v[14:17], v[186:189], v[134:137], v[2:5]
	v_mfma_f32_16x16x32_bf16 v[10:13], v[198:201], v[134:137], v[218:221]
	v_mfma_f32_16x16x32_bf16 v[2:5], v[230:233], v[134:137], v[130:133]
	v_mfma_f32_16x16x32_bf16 v[6:9], v[246:249], v[134:137], v[142:145]
	s_cbranch_vccz .LBB0_900
	s_nop 0
	v_cvt_pk_bf16_f32 v130, v126, v127
	v_cvt_pk_bf16_f32 v131, v128, v129
	s_mov_b64 s[28:29], 0
